# D2: D1 plus the per-step DMA issues interleaved under the QK^T / PV MFMAs (unconditional in PV loop)
# speedup vs baseline: 1.0197x; 1.0197x over previous
; #define SBAR() __builtin_amdgcn_sched_barrier(0)
; #define A2_LOADT(t) do { const size_t ro_ = (size_t)((t) * 64 + sr) * D + sc; \
;         sk0 = att::load8(c.K + ro_); sk1 = att::load8(c.K + ro_ + 32 * D); sv00 = att::load8(c.V0 + ro_); sv01 = att::load8(c.V0 + ro_ + 32 * D); sv10 = att::load8(c.V1 + ro_); sv11 = att::load8(c.V1 + ro_ + 32 * D); } while (0)
; __device__ __forceinline__ void attn2_block(const Blk& c, char* lds) {
;     ...
;         for (int s = 0; s <= NT; ++s) {
;             if (s + 1 < NT) A2_LOADT(s + 1);
;             SBAR();
.LBB0_544:
	s_add_i32 s85, s84, -1
	v_lshl_add_u64 v[172:173], v[168:169], 0, s[2:3]
	v_lshl_add_u64 v[174:175], v[170:171], 0, s[2:3]
	v_lshl_add_u64 v[176:177], v[164:165], 0, s[2:3]
	v_lshl_add_u64 v[178:179], v[166:167], 0, s[2:3]
	s_and_b32 s11, s85, 1
	s_lshl_b32 s11, s11, 15
	s_add_i32 s11, s11, s100
	s_andn2_b32 s101, 1, s85
	s_lshl_b32 s101, s101, 14
	s_add_i32 s101, s101, s100
	s_add_i32 s101, s101, 0x10000

; #define A2_WRITET(buf) do { char* kd_ = lds + L_K + (buf) * SHM_K; char* vd_ = lds + L_V + (buf) * 2 * SHM_V; \
;         *(bf16x8*)(kd_ + kws) = sk0; *(bf16x8*)(kd_ + kws + 32 * 256) = sk1; *(bf16x8*)(vd_ + vst0) = sv00; *(bf16x8*)(vd_ + vst1) = sv01; *(bf16x8*)(vd_ + SHM_V + vst0) = sv10; *(bf16x8*)(vd_ + SHM_V + vst1) = sv11; } while (0)
; template <int VB>
; __device__ __forceinline__ void pv_tile(f32x16* o, int vb0, bf16x8 pa0, bf16x8 pa1, bf16x8 pa2, bf16x8 pa3) {
;     ...
;     PV_D0(0); PV_D0(1); PV_D0(2); PV_D0(3);
; __device__ __forceinline__ void attn2_block(const Blk& c, char* lds) {
;     ...
;                 const char* pr = Pb + par * 4096 + lane * 16;
;                 const bf16x8 pa0 = *(const bf16x8*)(pr), pa1 = *(const bf16x8*)(pr + 1024), pa2 = *(const bf16x8*)(pr + 2048), pa3 = *(const bf16x8*)(pr + 3072);
;                 const int vb = vbase + par * 2 * SHM_V;
;                 att::pv_tile<0>(o, vb, pa0, pa1, pa2, pa3);
;                 att::pv_tile<0>(o + 4, vb + SHM_V, pa0, pa1, pa2, pa3);
;             }
;             __syncthreads();
;             if (s + 1 < NT) { asm volatile("s_waitcnt vmcnt(0)" ::: "memory"); A2_WRITET((s + 1) & 1); }
;             __syncthreads();
.LBB0_548:
	v_lshl_add_u32 v2, s85, 12, v230
	ds_read_b128 v[192:195], v2
	ds_read_b128 v[188:191], v2 offset:1024
	ds_read_b128 v[184:187], v2 offset:2048
	ds_read_b128 v[180:183], v2 offset:3072
	v_lshl_add_u32 v2, s85, 15, v231
	ds_read_b64_tr_b16 v[232:233], v2 offset:0
	ds_read_b64_tr_b16 v[234:235], v2 offset:0x800
	ds_read_b64_tr_b16 v[242:243], v2 offset:0x1000
	ds_read_b64_tr_b16 v[244:245], v2 offset:0x1800
	ds_read_b64_tr_b16 v[246:247], v2 offset:0x2000
	ds_read_b64_tr_b16 v[248:249], v2 offset:0x2800
	ds_read_b64_tr_b16 v[250:251], v2 offset:0x3000
	ds_read_b64_tr_b16 v[252:253], v2 offset:0x3800
	s_waitcnt lgkmcnt(0)
	s_waitcnt lgkmcnt(3)
	v_mfma_f32_32x32x16_bf16 v[116:131], v[192:195], v[232:235], v[116:131]
	s_mov_b32 m0, s11
	ds_read_b64_tr_b16 v[232:233], v2 offset:0x200
	ds_read_b64_tr_b16 v[234:235], v2 offset:0xa00
	s_waitcnt lgkmcnt(2)
	v_mfma_f32_32x32x16_bf16 v[116:131], v[188:191], v[242:245], v[116:131]
	global_load_lds_dwordx4 v[172:173], off
	ds_read_b64_tr_b16 v[242:243], v2 offset:0x1200
	ds_read_b64_tr_b16 v[244:245], v2 offset:0x1a00
	s_waitcnt lgkmcnt(1)
	v_mfma_f32_32x32x16_bf16 v[116:131], v[184:187], v[246:249], v[116:131]
	s_add_i32 m0, s11, 0x380
	ds_read_b64_tr_b16 v[246:247], v2 offset:0x2200
	ds_read_b64_tr_b16 v[248:249], v2 offset:0x2a00
	s_waitcnt lgkmcnt(0)
	v_mfma_f32_32x32x16_bf16 v[116:131], v[180:183], v[250:253], v[116:131]
	global_load_lds_dwordx4 v[172:173], off offset:128
	ds_read_b64_tr_b16 v[250:251], v2 offset:0x3200
	ds_read_b64_tr_b16 v[252:253], v2 offset:0x3a00
	s_waitcnt lgkmcnt(0)
	v_mfma_f32_32x32x16_bf16 v[100:115], v[192:195], v[232:235], v[100:115]
	s_add_i32 m0, s11, 0x4000
	ds_read_b64_tr_b16 v[232:233], v2 offset:0x400
	ds_read_b64_tr_b16 v[234:235], v2 offset:0xc00
	v_mfma_f32_32x32x16_bf16 v[100:115], v[188:191], v[242:245], v[100:115]
	global_load_lds_dwordx4 v[174:175], off
	ds_read_b64_tr_b16 v[242:243], v2 offset:0x1400
	ds_read_b64_tr_b16 v[244:245], v2 offset:0x1c00
	v_mfma_f32_32x32x16_bf16 v[100:115], v[184:187], v[246:249], v[100:115]
	s_add_i32 m0, s11, 0x4380
	ds_read_b64_tr_b16 v[246:247], v2 offset:0x2400
	ds_read_b64_tr_b16 v[248:249], v2 offset:0x2c00
	v_mfma_f32_32x32x16_bf16 v[100:115], v[180:183], v[250:253], v[100:115]
	global_load_lds_dwordx4 v[174:175], off offset:128
	ds_read_b64_tr_b16 v[250:251], v2 offset:0x3400
	ds_read_b64_tr_b16 v[252:253], v2 offset:0x3c00
	s_waitcnt lgkmcnt(0)
	v_mfma_f32_32x32x16_bf16 v[84:99], v[192:195], v[232:235], v[84:99]
	s_mov_b32 m0, s101
	ds_read_b64_tr_b16 v[232:233], v2 offset:0x600
	ds_read_b64_tr_b16 v[234:235], v2 offset:0xe00
	v_mfma_f32_32x32x16_bf16 v[84:99], v[188:191], v[242:245], v[84:99]
	global_load_lds_dwordx4 v[176:177], off
	ds_read_b64_tr_b16 v[242:243], v2 offset:0x1600
	ds_read_b64_tr_b16 v[244:245], v2 offset:0x1e00
	v_mfma_f32_32x32x16_bf16 v[84:99], v[184:187], v[246:249], v[84:99]
	ds_read_b64_tr_b16 v[246:247], v2 offset:0x2600
	ds_read_b64_tr_b16 v[248:249], v2 offset:0x2e00
	v_mfma_f32_32x32x16_bf16 v[84:99], v[180:183], v[250:253], v[84:99]
	global_load_lds_dwordx4 v[178:179], off offset:1024
	ds_read_b64_tr_b16 v[250:251], v2 offset:0x3600
	ds_read_b64_tr_b16 v[252:253], v2 offset:0x3e00
	s_waitcnt lgkmcnt(0)
	v_mfma_f32_32x32x16_bf16 v[68:83], v[192:195], v[232:235], v[68:83]
	v_add_u32_e32 v2, 0x4000, v2
	ds_read_b64_tr_b16 v[232:233], v2 offset:0
	ds_read_b64_tr_b16 v[234:235], v2 offset:0x800
	v_mfma_f32_32x32x16_bf16 v[68:83], v[188:191], v[242:245], v[68:83]
	ds_read_b64_tr_b16 v[242:243], v2 offset:0x1000
	ds_read_b64_tr_b16 v[244:245], v2 offset:0x1800
	v_mfma_f32_32x32x16_bf16 v[68:83], v[184:187], v[246:249], v[68:83]
	ds_read_b64_tr_b16 v[246:247], v2 offset:0x2000
	ds_read_b64_tr_b16 v[248:249], v2 offset:0x2800
	v_mfma_f32_32x32x16_bf16 v[68:83], v[180:183], v[250:253], v[68:83]
	ds_read_b64_tr_b16 v[250:251], v2 offset:0x3000
	ds_read_b64_tr_b16 v[252:253], v2 offset:0x3800
	s_waitcnt lgkmcnt(0)
	v_mfma_f32_32x32x16_bf16 v[52:67], v[192:195], v[232:235], v[52:67]
	ds_read_b64_tr_b16 v[232:233], v2 offset:0x200
	ds_read_b64_tr_b16 v[234:235], v2 offset:0xa00
	v_mfma_f32_32x32x16_bf16 v[52:67], v[188:191], v[242:245], v[52:67]
	ds_read_b64_tr_b16 v[242:243], v2 offset:0x1200
	ds_read_b64_tr_b16 v[244:245], v2 offset:0x1a00
	v_mfma_f32_32x32x16_bf16 v[52:67], v[184:187], v[246:249], v[52:67]
	ds_read_b64_tr_b16 v[246:247], v2 offset:0x2200
	ds_read_b64_tr_b16 v[248:249], v2 offset:0x2a00
	v_mfma_f32_32x32x16_bf16 v[52:67], v[180:183], v[250:253], v[52:67]
	ds_read_b64_tr_b16 v[250:251], v2 offset:0x3200
	ds_read_b64_tr_b16 v[252:253], v2 offset:0x3a00
	s_waitcnt lgkmcnt(0)
	v_mfma_f32_32x32x16_bf16 v[36:51], v[192:195], v[232:235], v[36:51]
	ds_read_b64_tr_b16 v[232:233], v2 offset:0x400
	ds_read_b64_tr_b16 v[234:235], v2 offset:0xc00
	v_mfma_f32_32x32x16_bf16 v[36:51], v[188:191], v[242:245], v[36:51]
	ds_read_b64_tr_b16 v[242:243], v2 offset:0x1400
	ds_read_b64_tr_b16 v[244:245], v2 offset:0x1c00
	v_mfma_f32_32x32x16_bf16 v[36:51], v[184:187], v[246:249], v[36:51]
	ds_read_b64_tr_b16 v[246:247], v2 offset:0x2400
	ds_read_b64_tr_b16 v[248:249], v2 offset:0x2c00
	v_mfma_f32_32x32x16_bf16 v[36:51], v[180:183], v[250:253], v[36:51]
	ds_read_b64_tr_b16 v[250:251], v2 offset:0x3400
	ds_read_b64_tr_b16 v[252:253], v2 offset:0x3c00
	s_waitcnt lgkmcnt(0)
	v_mfma_f32_32x32x16_bf16 v[20:35], v[192:195], v[232:235], v[20:35]
	ds_read_b64_tr_b16 v[232:233], v2 offset:0x600
	ds_read_b64_tr_b16 v[234:235], v2 offset:0xe00
	v_mfma_f32_32x32x16_bf16 v[20:35], v[188:191], v[242:245], v[20:35]
	ds_read_b64_tr_b16 v[242:243], v2 offset:0x1600
	ds_read_b64_tr_b16 v[244:245], v2 offset:0x1e00
	v_mfma_f32_32x32x16_bf16 v[20:35], v[184:187], v[246:249], v[20:35]
	ds_read_b64_tr_b16 v[246:247], v2 offset:0x2600
	ds_read_b64_tr_b16 v[248:249], v2 offset:0x2e00
	v_mfma_f32_32x32x16_bf16 v[20:35], v[180:183], v[250:253], v[20:35]
	ds_read_b64_tr_b16 v[250:251], v2 offset:0x3600
	ds_read_b64_tr_b16 v[252:253], v2 offset:0x3e00
	s_waitcnt lgkmcnt(0)
	v_mfma_f32_32x32x16_bf16 v[4:19], v[192:195], v[232:235], v[4:19]
	s_waitcnt vmcnt(0)
	s_barrier
	v_mfma_f32_32x32x16_bf16 v[4:19], v[188:191], v[242:245], v[4:19]
	v_mfma_f32_32x32x16_bf16 v[4:19], v[184:187], v[246:249], v[4:19]
	v_mfma_f32_32x32x16_bf16 v[4:19], v[180:183], v[250:253], v[4:19]
	s_branch .LBB0_543

; #define SBAR() __builtin_amdgcn_sched_barrier(0)
; #define A2_LOADT(t) do { const size_t ro_ = (size_t)((t) * 64 + sr) * D + sc; \
;         sk0 = att::load8(c.K + ro_); sk1 = att::load8(c.K + ro_ + 32 * D); sv00 = att::load8(c.V0 + ro_); sv01 = att::load8(c.V0 + ro_ + 32 * D); sv10 = att::load8(c.V1 + ro_); sv11 = att::load8(c.V1 + ro_ + 32 * D); } while (0)
; __device__ __forceinline__ void qkt_rt(f32x16& p0, f32x16& p1, const char* Kb, int r32, int hi, const bf16x8* qr) {
;     p0 = f32x16{}; p1 = f32x16{};
;     const char* kb[4];
; #pragma unroll
;     for (int dd = 0; dd < 4; ++dd) kb[dd] = Kb + KSWZ(r32, (dd * 16 + hi * 8) * 2);
; #pragma unroll
;     for (int d0 = 0; d0 < 8; ++d0) { const char* a = kb[d0 & 3] + (d0 >> 2) * 128;
;         bf16x8 b0 = *reinterpret_cast<const bf16x8*>(a);
;         bf16x8 b1 = *reinterpret_cast<const bf16x8*>(a + 32 * 256);
;         p0 = __builtin_amdgcn_mfma_f32_32x32x16_bf16(b0, qr[d0], p0, 0, 0, 0);
;         p1 = __builtin_amdgcn_mfma_f32_32x32x16_bf16(b1, qr[d0], p1, 0, 0, 0); }
; }
; __device__ __forceinline__ void attn2_block(const Blk& c, char* lds) {
;     ...
;         for (int s = 0; s <= NT; ++s) {
;             const int par = s & 1;
;             if (s + 1 < NT) A2_LOADT(s + 1);
;             SBAR();
;             if (s < NT) {
;                 f32x16 p0, p1; float mn, al; bf16x8 pa0, pa1, pa2, pa3;
;                 qkt_rt(p0, p1, lds + L_K + par * SHM_K, r32, hi, qr);
;                 const int kb_ = s * 64;
.LBB0_552:
	s_and_b32 s88, s30, 1
	s_lshl_b32 s10, s88, 15
	s_add_i32 s10, s10, s100
	s_xor_b32 s11, s88, 1
	s_lshl_b32 s11, s11, 14
	s_add_i32 s11, s11, s100
	s_add_i32 s11, s11, 0x10000
	s_lshl_b32 s17, s88, 14
	s_add_i32 s17, s17, 0x10000
	v_lshl_add_u64 v[52:53], v[168:169], 0, s[82:83]
	v_lshl_add_u64 v[54:55], v[170:171], 0, s[82:83]
	v_lshl_add_u64 v[56:57], v[164:165], 0, s[82:83]
	v_lshl_add_u64 v[58:59], v[166:167], 0, s[82:83]
	v_add3_u32 v40, s17, v121, v119
	ds_read_b128 v[4:7], v40
	v_add3_u32 v41, s17, v122, v119
	ds_read_b128 v[36:39], v41
	v_add3_u32 v42, s17, v123, v119
	v_add3_u32 v43, s17, v124, v119
	s_mov_b32 m0, s10
	s_waitcnt lgkmcnt(1)
	v_mfma_f32_32x32x16_bf16 v[20:35], v[4:7], v[104:107], 0
	ds_read_b128 v[4:7], v40 offset:8192
	global_load_lds_dwordx4 v[52:53], off
	s_add_i32 m0, s10, 0x380
	s_waitcnt lgkmcnt(1)
	v_mfma_f32_32x32x16_bf16 v[20:35], v[36:39], v[100:103], v[20:35]
	ds_read_b128 v[36:39], v41 offset:8192
	global_load_lds_dwordx4 v[52:53], off offset:128
	s_add_i32 m0, s10, 0x4000
	s_waitcnt lgkmcnt(1)
	v_mfma_f32_32x32x16_bf16 v[4:19], v[4:7], v[104:107], 0
	global_load_lds_dwordx4 v[54:55], off
	s_add_i32 m0, s10, 0x4380
	s_waitcnt lgkmcnt(0)
	v_mfma_f32_32x32x16_bf16 v[4:19], v[36:39], v[100:103], v[4:19]
	ds_read_b128 v[36:39], v42
	global_load_lds_dwordx4 v[54:55], off offset:128
	s_mov_b32 m0, s11
	s_waitcnt lgkmcnt(0)
	v_mfma_f32_32x32x16_bf16 v[20:35], v[36:39], v[96:99], v[20:35]
	ds_read_b128 v[36:39], v42 offset:8192
	global_load_lds_dwordx4 v[56:57], off
	s_waitcnt lgkmcnt(0)
	v_mfma_f32_32x32x16_bf16 v[4:19], v[36:39], v[96:99], v[4:19]
	ds_read_b128 v[36:39], v43
	global_load_lds_dwordx4 v[58:59], off offset:1024
	s_waitcnt lgkmcnt(0)
	v_mfma_f32_32x32x16_bf16 v[20:35], v[36:39], v[92:95], v[20:35]
	ds_read_b128 v[36:39], v43 offset:8192
	s_waitcnt lgkmcnt(0)
	v_mfma_f32_32x32x16_bf16 v[4:19], v[36:39], v[92:95], v[4:19]
	ds_read_b128 v[36:39], v40 offset:128
	s_waitcnt lgkmcnt(0)
	v_mfma_f32_32x32x16_bf16 v[20:35], v[36:39], v[88:91], v[20:35]
	ds_read_b128 v[36:39], v40 offset:8320
	s_waitcnt lgkmcnt(0)
	v_mfma_f32_32x32x16_bf16 v[4:19], v[36:39], v[88:91], v[4:19]
	ds_read_b128 v[36:39], v41 offset:128
	s_waitcnt lgkmcnt(0)
	v_mfma_f32_32x32x16_bf16 v[20:35], v[36:39], v[84:87], v[20:35]
	ds_read_b128 v[36:39], v41 offset:8320
	s_waitcnt lgkmcnt(0)
	v_mfma_f32_32x32x16_bf16 v[4:19], v[36:39], v[84:87], v[4:19]
	ds_read_b128 v[36:39], v42 offset:128
	s_waitcnt lgkmcnt(0)
	v_mfma_f32_32x32x16_bf16 v[20:35], v[36:39], v[80:83], v[20:35]
	ds_read_b128 v[36:39], v42 offset:8320
	s_waitcnt lgkmcnt(0)
	v_mfma_f32_32x32x16_bf16 v[4:19], v[36:39], v[80:83], v[4:19]
	ds_read_b128 v[36:39], v43 offset:128
	s_waitcnt lgkmcnt(0)
	v_mfma_f32_32x32x16_bf16 v[20:35], v[36:39], v[76:79], v[20:35]
	ds_read_b128 v[36:39], v43 offset:8320
	s_waitcnt lgkmcnt(0)
	v_mfma_f32_32x32x16_bf16 v[4:19], v[36:39], v[76:79], v[4:19]
	s_add_i32 s10, s84, 63
	s_cmp_le_i32 s10, s86
	s_cbranch_scc1 .LBB0_586
; __device__ __forceinline__ void bias_mask_tile(f32x16& p0, f32x16& p1, int dq, const float* bt) {
;     const float NEG = -__builtin_inff();
; #pragma unroll
;     for (int r = 0; r < 16; ++r) {
;         const int c = (r & 3) + 8 * (r >> 2);
;         const int d0 = dq - c, d1 = dq - c - 32;
;         const unsigned i0 = (unsigned)d0 < 255u ? (unsigned)d0 : 255u, i1 = (unsigned)d1 < 255u ? (unsigned)d1 : 255u;
;         const float b0 = bt[i0], b1 = bt[i1];
;         p0[r] = d0 >= 0 ? p0[r] + b0 : NEG;
;         p1[r] = d1 >= 0 ? p1[r] + b1 : NEG;
;     }
; }
	v_add_u32_e32 v115, 27, v125
	v_lshl_add_u32 v36, v115, 2, s64
	v_add_u32_e32 v36, 0xffffff14, v36
	ds_read_b32 v132, v36 offset:236
	ds_read_b32 v133, v36 offset:232
	ds_read_b32 v134, v36 offset:228
	ds_read_b32 v135, v36 offset:224
	ds_read_b32 v136, v36 offset:204
	ds_read_b32 v137, v36 offset:200
	ds_read_b32 v138, v36 offset:196
	ds_read_b32 v139, v36 offset:192
	ds_read_b32 v140, v36 offset:172
	ds_read_b32 v141, v36 offset:168
	ds_read_b32 v142, v36 offset:164
	ds_read_b32 v143, v36 offset:160
	ds_read_b32 v144, v36 offset:140
	ds_read_b32 v145, v36 offset:136
	ds_read_b32 v146, v36 offset:132
	v_cmp_lt_i32_e32 vcc, -1, v115
	v_cmp_lt_i32_e64 s[16:17], 0, v115
	s_waitcnt lgkmcnt(14)
	v_add_f32_e32 v20, v20, v132
	ds_read_b32 v147, v36 offset:128
	s_waitcnt lgkmcnt(14)
	v_add_f32_e32 v21, v21, v133
	ds_read_b32 v148, v36 offset:108
	v_cndmask_b32_e32 v20, v240, v20, vcc
	v_cndmask_b32_e64 v21, v240, v21, s[16:17]
	v_cmp_lt_i32_e32 vcc, 1, v115
	v_cmp_lt_i32_e64 s[16:17], 2, v115
	s_waitcnt lgkmcnt(14)
	v_add_f32_e32 v22, v22, v134
	ds_read_b32 v149, v36 offset:104
	s_waitcnt lgkmcnt(14)
	v_add_f32_e32 v23, v23, v135
	ds_read_b32 v150, v36 offset:100
	v_cndmask_b32_e32 v22, v240, v22, vcc
	v_cndmask_b32_e64 v23, v240, v23, s[16:17]
	v_cmp_lt_i32_e32 vcc, 7, v115
	v_cmp_lt_i32_e64 s[16:17], 8, v115
	s_waitcnt lgkmcnt(14)
	v_add_f32_e32 v24, v24, v136
	ds_read_b32 v151, v36 offset:96
	s_waitcnt lgkmcnt(14)
	v_add_f32_e32 v25, v25, v137
	ds_read_b32 v152, v36 offset:76
	v_cndmask_b32_e32 v24, v240, v24, vcc
	v_cndmask_b32_e64 v25, v240, v25, s[16:17]
	v_cmp_lt_i32_e32 vcc, 9, v115
	v_cmp_lt_i32_e64 s[16:17], 10, v115
	s_waitcnt lgkmcnt(14)
	v_add_f32_e32 v26, v26, v138
	ds_read_b32 v153, v36 offset:72
	s_waitcnt lgkmcnt(14)
	v_add_f32_e32 v27, v27, v139
	ds_read_b32 v154, v36 offset:68
	v_cndmask_b32_e32 v26, v240, v26, vcc
	v_cndmask_b32_e64 v27, v240, v27, s[16:17]
	v_cmp_lt_i32_e32 vcc, 15, v115
	v_cmp_lt_i32_e64 s[16:17], 16, v115
	s_waitcnt lgkmcnt(14)
	v_add_f32_e32 v28, v28, v140
	ds_read_b32 v155, v36 offset:64
	s_waitcnt lgkmcnt(14)
	v_add_f32_e32 v29, v29, v141
	ds_read_b32 v60, v36 offset:44
	v_cndmask_b32_e32 v28, v240, v28, vcc
	v_cndmask_b32_e64 v29, v240, v29, s[16:17]
	v_cmp_lt_i32_e32 vcc, 17, v115
	v_cmp_lt_i32_e64 s[16:17], 18, v115
	s_waitcnt lgkmcnt(14)
	v_add_f32_e32 v30, v30, v142
	ds_read_b32 v61, v36 offset:40
	s_waitcnt lgkmcnt(14)
	v_add_f32_e32 v31, v31, v143
	ds_read_b32 v62, v36 offset:36
	v_cndmask_b32_e32 v30, v240, v30, vcc
	v_cndmask_b32_e64 v31, v240, v31, s[16:17]
	v_cmp_lt_i32_e32 vcc, 23, v115
	v_cmp_lt_i32_e64 s[16:17], 24, v115
	s_waitcnt lgkmcnt(14)
	v_add_f32_e32 v32, v32, v144
	ds_read_b32 v63, v36 offset:32
	s_waitcnt lgkmcnt(14)
	v_add_f32_e32 v33, v33, v145
	ds_read_b32 v64, v36 offset:12
	v_cndmask_b32_e32 v32, v240, v32, vcc
	v_cndmask_b32_e64 v33, v240, v33, s[16:17]
	v_cmp_lt_i32_e32 vcc, 25, v115
	v_cmp_lt_i32_e64 s[16:17], 26, v115
	s_waitcnt lgkmcnt(14)
	v_add_f32_e32 v34, v34, v146
	ds_read_b32 v65, v36 offset:8
	s_waitcnt lgkmcnt(14)
	v_add_f32_e32 v35, v35, v147
	ds_read_b32 v66, v36 offset:4
	v_cndmask_b32_e32 v34, v240, v34, vcc
	v_cndmask_b32_e64 v35, v240, v35, s[16:17]
	v_cmp_lt_i32_e32 vcc, 31, v115
	v_cmp_lt_i32_e64 s[16:17], 32, v115
	s_waitcnt lgkmcnt(14)
	v_add_f32_e32 v4, v4, v148
	ds_read_b32 v67, v36 offset:0
	s_waitcnt lgkmcnt(14)
	v_add_f32_e32 v5, v5, v149
	v_cndmask_b32_e32 v4, v240, v4, vcc
	v_cndmask_b32_e64 v5, v240, v5, s[16:17]
	v_cmp_lt_i32_e32 vcc, 33, v115
	v_cmp_lt_i32_e64 s[16:17], 34, v115
	s_waitcnt lgkmcnt(13)
	v_add_f32_e32 v6, v6, v150
	s_waitcnt lgkmcnt(12)
	v_add_f32_e32 v7, v7, v151
	v_cndmask_b32_e32 v6, v240, v6, vcc
	v_cndmask_b32_e64 v7, v240, v7, s[16:17]
	v_cmp_lt_i32_e32 vcc, 39, v115
	v_cmp_lt_i32_e64 s[16:17], 40, v115
	s_waitcnt lgkmcnt(11)
	v_add_f32_e32 v8, v8, v152
	s_waitcnt lgkmcnt(10)
	v_add_f32_e32 v9, v9, v153
	v_cndmask_b32_e32 v8, v240, v8, vcc
	v_cndmask_b32_e64 v9, v240, v9, s[16:17]
	v_cmp_lt_i32_e32 vcc, 41, v115
	v_cmp_lt_i32_e64 s[16:17], 42, v115
	s_waitcnt lgkmcnt(9)
	v_add_f32_e32 v10, v10, v154
	s_waitcnt lgkmcnt(8)
	v_add_f32_e32 v11, v11, v155
	v_cndmask_b32_e32 v10, v240, v10, vcc
	v_cndmask_b32_e64 v11, v240, v11, s[16:17]
	v_cmp_lt_i32_e32 vcc, 47, v115
	v_cmp_lt_i32_e64 s[16:17], 48, v115
	s_waitcnt lgkmcnt(7)
	v_add_f32_e32 v12, v12, v60
	s_waitcnt lgkmcnt(6)
	v_add_f32_e32 v13, v13, v61
	v_cndmask_b32_e32 v12, v240, v12, vcc
	v_cndmask_b32_e64 v13, v240, v13, s[16:17]
	v_cmp_lt_i32_e32 vcc, 49, v115
	v_cmp_lt_i32_e64 s[16:17], 50, v115
	s_waitcnt lgkmcnt(5)
	v_add_f32_e32 v14, v14, v62
	s_waitcnt lgkmcnt(4)
	v_add_f32_e32 v15, v15, v63
	v_cndmask_b32_e32 v14, v240, v14, vcc
	v_cndmask_b32_e64 v15, v240, v15, s[16:17]
	v_cmp_lt_i32_e32 vcc, 55, v115
	v_cmp_lt_i32_e64 s[16:17], 56, v115
	s_waitcnt lgkmcnt(3)
	v_add_f32_e32 v16, v16, v64
	s_waitcnt lgkmcnt(2)
	v_add_f32_e32 v17, v17, v65
	v_cndmask_b32_e32 v16, v240, v16, vcc
	v_cndmask_b32_e64 v17, v240, v17, s[16:17]
	v_cmp_lt_i32_e32 vcc, 57, v115
	v_cmp_lt_i32_e64 s[16:17], 58, v115
	s_waitcnt lgkmcnt(1)
	v_add_f32_e32 v18, v18, v66
	s_waitcnt lgkmcnt(0)
	v_add_f32_e32 v19, v19, v67
	v_cndmask_b32_e32 v18, v240, v18, vcc
	v_cndmask_b32_e64 v19, v240, v19, s[16:17]
